# job3 loop MFMA/VALU interleave: second-half exp2, row-sum adds, second fragment conversions and l update ride in the gaps of PV MFMAs 0-7
# baseline (speedup 1.0000x reference)
.LBB0_946:
	v_sub_f32_e32 v131, v146, v229
	v_sub_f32_e32 v147, v147, v229
	v_exp_f32_e32 v131, v131
	v_exp_f32_e32 v147, v147
	v_sub_f32_e32 v132, v132, v229
	v_sub_f32_e32 v133, v133, v229
	v_exp_f32_e32 v132, v132
	v_exp_f32_e32 v133, v133
	v_sub_f32_e32 v134, v134, v229
	v_sub_f32_e32 v135, v135, v229
	v_exp_f32_e32 v148, v134
	v_exp_f32_e32 v135, v135
	v_sub_f32_e32 v136, v136, v229
	v_sub_f32_e32 v137, v137, v229
	v_exp_f32_e32 v146, v136
	v_exp_f32_e32 v149, v137
	v_sub_f32_e32 v138, v138, v229
	v_sub_f32_e32 v139, v139, v229
	v_exp_f32_e32 v150, v138
	v_exp_f32_e32 v151, v139
	v_cvt_pk_bf16_f32 v136, v131, v147
	v_cvt_pk_bf16_f32 v137, v132, v133
	v_cvt_pk_bf16_f32 v138, v148, v135
	v_cvt_pk_bf16_f32 v139, v146, v149
	v_add_f32_e32 v134, v131, v147
	v_add_f32_e32 v134, v132, v134
	s_waitcnt lgkmcnt(6)
	v_mfma_f32_32x32x16_bf16 v[114:129], v[232:235], v[136:139], v[114:129]
	ds_read_b64_tr_b16 v[232:233], v222 offset:256
	ds_read_b64_tr_b16 v[234:235], v222 offset:4992
	v_sub_f32_e32 v140, v140, v229
	v_add_f32_e32 v134, v133, v134
	v_exp_f32_e32 v140, v140
	s_waitcnt lgkmcnt(6)
	v_mfma_f32_32x32x16_bf16 v[98:113], v[236:239], v[136:139], v[98:113]
	ds_read_b64_tr_b16 v[236:237], v222 offset:320
	ds_read_b64_tr_b16 v[238:239], v222 offset:5056
	v_add_f32_e32 v134, v148, v134
	v_sub_f32_e32 v141, v141, v229
	v_add_f32_e32 v134, v135, v134
	v_exp_f32_e32 v141, v141
	s_waitcnt lgkmcnt(6)
	v_mfma_f32_32x32x16_bf16 v[82:97], v[240:243], v[136:139], v[82:97]
	ds_read_b64_tr_b16 v[240:241], v222 offset:384
	ds_read_b64_tr_b16 v[242:243], v222 offset:5120
	v_add_f32_e32 v134, v146, v134
	v_sub_f32_e32 v142, v142, v229
	v_add_f32_e32 v134, v149, v134
	v_exp_f32_e32 v142, v142
	s_waitcnt lgkmcnt(6)
	v_mfma_f32_32x32x16_bf16 v[66:81], v[246:249], v[136:139], v[66:81]
	ds_read_b64_tr_b16 v[246:247], v222 offset:448
	ds_read_b64_tr_b16 v[248:249], v222 offset:5184
	v_add_f32_e32 v134, v150, v134
	v_sub_f32_e32 v143, v143, v229
	v_add_f32_e32 v134, v151, v134
	v_exp_f32_e32 v143, v143
	s_waitcnt lgkmcnt(6)
	v_mfma_f32_32x32x16_bf16 v[50:65], v[232:235], v[136:139], v[50:65]
	ds_read_b64_tr_b16 v[232:233], v222 offset:9472
	ds_read_b64_tr_b16 v[234:235], v222 offset:14208
	v_add_f32_e32 v134, v140, v134
	v_sub_f32_e32 v144, v144, v229
	v_add_f32_e32 v134, v141, v134
	v_exp_f32_e32 v144, v144
	s_waitcnt lgkmcnt(6)
	v_mfma_f32_32x32x16_bf16 v[34:49], v[236:239], v[136:139], v[34:49]
	ds_read_b64_tr_b16 v[236:237], v222 offset:9536
	ds_read_b64_tr_b16 v[238:239], v222 offset:14272
	v_add_f32_e32 v134, v142, v134
	v_sub_f32_e32 v145, v145, v229
	v_add_f32_e32 v134, v143, v134
	v_exp_f32_e32 v145, v145
	s_waitcnt lgkmcnt(6)
	v_mfma_f32_32x32x16_bf16 v[18:33], v[240:243], v[136:139], v[18:33]
	ds_read_b64_tr_b16 v[240:241], v222 offset:9600
	ds_read_b64_tr_b16 v[242:243], v222 offset:14336
	v_add_f32_e32 v134, v144, v134
	v_cvt_pk_bf16_f32 v131, v140, v141
	v_add_f32_e32 v134, v145, v134
	v_fmac_f32_e32 v134, v211, v130
	s_waitcnt lgkmcnt(6)
	v_mfma_f32_32x32x16_bf16 v[2:17], v[246:249], v[136:139], v[2:17]
	ds_read_b64_tr_b16 v[246:247], v222 offset:9664
	ds_read_b64_tr_b16 v[248:249], v222 offset:14400
	v_cvt_pk_bf16_f32 v130, v150, v151
	v_cvt_pk_bf16_f32 v132, v142, v143
	v_cvt_pk_bf16_f32 v133, v144, v145
	v_mov_b32_e32 v211, v134
	s_nop 1
	s_waitcnt lgkmcnt(6)
	v_mfma_f32_32x32x16_bf16 v[114:129], v[232:235], v[130:133], v[114:129]
	ds_read_b64_tr_b16 v[232:233], v222 offset:9728
	ds_read_b64_tr_b16 v[234:235], v222 offset:14464
	s_waitcnt lgkmcnt(6)
	v_mfma_f32_32x32x16_bf16 v[98:113], v[236:239], v[130:133], v[98:113]
	ds_read_b64_tr_b16 v[236:237], v222 offset:9792
	ds_read_b64_tr_b16 v[238:239], v222 offset:14528
	s_waitcnt lgkmcnt(6)
	v_mfma_f32_32x32x16_bf16 v[82:97], v[240:243], v[130:133], v[82:97]
	ds_read_b64_tr_b16 v[240:241], v222 offset:9856
	ds_read_b64_tr_b16 v[242:243], v222 offset:14592
	s_waitcnt lgkmcnt(6)
	v_mfma_f32_32x32x16_bf16 v[66:81], v[246:249], v[130:133], v[66:81]
	ds_read_b64_tr_b16 v[246:247], v222 offset:9920
	ds_read_b64_tr_b16 v[248:249], v222 offset:14656
	s_waitcnt lgkmcnt(6)
	v_mfma_f32_32x32x16_bf16 v[50:65], v[232:235], v[130:133], v[50:65]
	s_waitcnt lgkmcnt(4)
	v_mfma_f32_32x32x16_bf16 v[34:49], v[236:239], v[130:133], v[34:49]
	s_waitcnt lgkmcnt(2)
	v_mfma_f32_32x32x16_bf16 v[18:33], v[240:243], v[130:133], v[18:33]
	s_waitcnt lgkmcnt(0)
	v_mfma_f32_32x32x16_bf16 v[2:17], v[246:249], v[130:133], v[2:17]
	s_branch .LBB0_948
